# latent attention: one barrier per key tile (V DMA at half top), counted lgkmcnt waits in P.V, QK^T operand reads issued one k-step ahead (double-buffered in freed VGPRs)
# speedup vs baseline: 1.0111x; 1.0034x over previous
.LBB0_853:
	s_and_b64 vcc, exec, s[0:1]
	s_cbranch_vccz .LBB0_820
	s_ashr_i32 s14, s49, 5
	s_ashr_i32 s15, s14, 31
	s_lshl_b32 s0, s49, 8
	s_lshl_b64 s[42:43], s[14:15], 11
	s_and_b32 s0, s0, 0x700
	s_or_b32 s42, s42, s0
	s_mul_i32 s0, s43, 0x600
	s_mul_hi_u32 s1, s42, 0x600
	s_bfe_u32 s4, s49, 0x20003
	s_add_i32 s1, s1, s0
	s_mul_i32 s0, s42, 0x600
	s_add_u32 s0, s84, s0
	s_addc_u32 s1, s85, s1
	s_mul_i32 s2, s4, 0x180
	s_add_u32 s16, s0, s2
	s_addc_u32 s17, s1, 0
	v_readlane_b32 s0, v251, 48
	v_readlane_b32 s1, v251, 49
	s_add_u32 s2, s0, s2
	s_addc_u32 s8, s1, 0
	s_lshl_b32 s7, s4, 7
	s_lshl_b32 s0, s4, 8
	v_readlane_b32 s10, v253, 7
	v_mov_b32_e32 v170, v0
	v_readlane_b32 s11, v253, 8
	s_add_u32 s9, s10, s0
	s_addc_u32 s10, s11, 0
	v_ashrrev_i32_e32 v161, 6, v170
	v_and_b32_e32 v172, 31, v170
	v_and_b32_e32 v2, 0x3fffffc0, v170
	s_add_i32 s1, 0, 0x14000
	v_lshlrev_b32_e32 v160, 5, v161
	v_bfe_u32 v173, v170, 5, 1
	v_lshl_add_u32 v64, v2, 2, s1
	v_or_b32_e32 v4, v160, v172
	s_waitcnt lgkmcnt(0)
	v_mov_b64_e32 v[2:3], s[16:17]
	s_movk_i32 s11, 0x600
	v_mad_i64_i32 v[2:3], s[16:17], v4, s11, v[2:3]
	v_lshlrev_b32_e32 v62, 4, v173
	v_mov_b32_e32 v63, v99
	v_lshl_add_u64 v[6:7], v[2:3], 0, v[62:63]
	v_lshlrev_b32_e32 v2, 12, v161
	s_add_i32 s1, 0, 0x14800
	v_lshlrev_b32_e32 v3, 7, v172
	global_load_dwordx4 v[128:131], v[6:7], off
	global_load_dwordx4 v[124:127], v[6:7], off offset:32
	global_load_dwordx4 v[120:123], v[6:7], off offset:64
	global_load_dwordx4 v[116:119], v[6:7], off offset:96
	global_load_dwordx4 v[112:115], v[6:7], off offset:128
	global_load_dwordx4 v[108:111], v[6:7], off offset:160
	global_load_dwordx4 v[104:107], v[6:7], off offset:192
	global_load_dwordx4 v[100:103], v[6:7], off offset:224
	v_add3_u32 v51, s1, v2, v3
	global_load_dwordx4 v[2:5], v[6:7], off offset:256
	global_load_dwordx4 v[132:135], v[6:7], off offset:288
	global_load_dwordx4 v[136:139], v[6:7], off offset:320
	global_load_dwordx4 v[140:143], v[6:7], off offset:352
	v_bitop3_b32 v8, v173, v170, 7 bitop3:0x78
	v_lshl_add_u32 v8, v8, 4, v51
	v_lshlrev_b32_e32 v14, 4, v170
	v_and_b32_e32 v50, 0x70, v14
	s_movk_i32 s1, 0x60
	s_movk_i32 s18, 0x180
	s_lshl_b32 s12, s14, 8
	s_add_i32 s0, s12, 0x4000
	s_lshl_b32 s13, s14, 11
	s_cmp_lg_u32 0, -1
	s_mul_i32 s15, s14, 0x60000
	s_cselect_b32 s14, 0, 0
	v_and_b32_e32 v171, 63, v170
	v_mul_u32_u24_e32 v55, 0x180, v172
	v_or_b32_e32 v52, 32, v62
	v_bitop3_b32 v56, v52, v55, v50 bitop3:0xde
	v_add_u32_e32 v184, 0, v56
	v_or_b32_e32 v53, 64, v62
	v_or_b32_e32 v54, 0x60, v62
	s_mov_b32 s68, s69
	s_mov_b32 s70, s69
	s_mov_b32 s71, s69
	s_mov_b32 s72, s69
	s_mov_b32 s73, s69
	s_mov_b32 s74, s69
	s_mov_b32 s75, s69
	s_mov_b32 s76, s69
	s_mov_b32 s77, s69
	s_mov_b32 s78, s69
	s_mov_b32 s79, s69
	s_mov_b32 s80, s69
	s_mov_b32 s81, s69
	s_mov_b32 s82, s69
	s_mov_b32 s83, s69
	v_lshl_add_u32 v197, v172, 2, v64
	v_add_u32_e32 v193, v64, v62
	v_mov_b32_e32 v212, 0x358637bd
	v_mov_b32_e32 v200, 0xff
	v_mov_b32_e32 v202, 0x1b00
	v_mov_b32_e32 v201, 0x600
	v_mov_b32_e32 v203, 0x260
	v_mov_b32_e32 v169, v99
	v_mov_b32_e32 v163, v99
	v_mov_b32_e32 v165, v99
	v_mov_b32_e32 v167, v99
	v_cmp_gt_u32_e64 s[38:39], 32, v171
	v_mov_b32_e32 v198, 0
	s_waitcnt vmcnt(0)
	ds_write_b128 v8, v[2:5]
	v_bitop3_b32 v8, v62, v50, 32 bitop3:0x36
	v_add_u32_e32 v176, v51, v8
	v_bitop3_b32 v8, v62, v50, 64 bitop3:0x36
	v_add_u32_e32 v177, v51, v8
	ds_write_b128 v176, v[132:135]
	ds_write_b128 v177, v[136:139]
	v_bitop3_b32 v6, v62, v50, s1 bitop3:0x36
	v_add_u32_e32 v175, v51, v6
	s_mov_b32 s1, 0x2aaaaaab
	ds_write_b128 v175, v[140:143]
	v_ashrrev_i32_e32 v2, 4, v170
	v_and_b32_e32 v5, 0xfffff0, v2
	v_lshlrev_b32_e32 v6, 1, v2
	v_and_or_b32 v5, v6, 8, v5
	v_lshrrev_b32_e32 v6, 1, v2
	v_and_b32_e32 v7, 3, v2
	v_and_or_b32 v6, v6, 4, v7
	v_add_u32_e32 v7, 32, v2
	v_and_b32_e32 v8, 0xfffff0, v7
	v_lshlrev_b32_e32 v7, 1, v7
	v_lshlrev_b32_e32 v3, 3, v170
	v_and_or_b32 v7, v7, 8, v8
	v_and_b32_e32 v4, 0x78, v3
	v_lshrrev_b32_e32 v5, 1, v5
	v_bfe_u32 v3, v3, 5, 2
	v_lshrrev_b32_e32 v7, 1, v7
	v_or_b32_e32 v5, v5, v3
	v_or_b32_e32 v3, v7, v3
	v_mul_hi_i32 v7, v170, s1
	v_lshrrev_b32_e32 v8, 31, v7
	v_ashrrev_i32_e32 v7, 2, v7
	v_add_u32_e32 v7, v7, v8
	v_mul_lo_u32 v8, v7, 24
	v_sub_u32_e32 v8, v170, v8
	v_mul_lo_u32 v9, v7, s11
	v_lshl_add_u32 v162, v8, 4, v9
	v_mul_lo_u32 v9, v7, s18
	v_bitop3_b32 v7, v7, v8, 7 bitop3:0x6c
	v_lshl_add_u32 v15, v7, 4, v9
	v_add_u32_e32 v7, 0x200, v170
	v_mul_hi_i32 v8, v7, s1
	v_lshrrev_b32_e32 v9, 31, v8
	v_ashrrev_i32_e32 v8, 2, v8
	v_add_u32_e32 v8, v8, v9
	v_mul_lo_u32 v9, v8, 24
	v_sub_u32_e32 v7, v7, v9
	v_mul_lo_u32 v9, v8, s11
	v_lshl_add_u32 v164, v7, 4, v9
	v_mul_lo_u32 v9, v8, s18
	v_bitop3_b32 v7, v8, v7, 7 bitop3:0x6c
	v_lshl_add_u32 v24, v7, 4, v9
	v_add_u32_e32 v7, 0x400, v170
	v_mul_hi_i32 v8, v7, s1
	v_lshrrev_b32_e32 v9, 31, v8
	v_ashrrev_i32_e32 v8, 2, v8
	v_add_u32_e32 v8, v8, v9
	v_mul_lo_u32 v9, v8, 24
	v_sub_u32_e32 v7, v7, v9
	v_mul_lo_u32 v9, v8, s11
	v_lshlrev_b32_e32 v4, 1, v4
	v_lshl_add_u32 v166, v7, 4, v9
	v_mul_lo_u32 v9, v8, s18
	v_bitop3_b32 v7, v8, v7, 7 bitop3:0x6c
	s_ashr_i32 s1, s0, 31
	v_lshlrev_b32_e32 v6, 6, v6
	v_lshlrev_b32_e32 v3, 9, v3
	v_lshl_add_u32 v25, v7, 4, v9
	v_and_b32_e32 v7, 48, v4
	s_lshl_b64 s[16:17], s[0:1], 10
	v_or3_b32 v27, v3, v6, v7
	v_lshl_or_b32 v98, v2, 10, v4
	v_lshlrev_b32_e32 v2, 3, v171
	v_and_b32_e32 v3, 0xc0, v14
	v_lshlrev_b32_e32 v4, 1, v170
	s_add_u32 s16, s9, s16
	v_lshlrev_b32_e32 v5, 9, v5
	v_and_or_b32 v3, v2, 24, v3
	v_and_b32_e32 v4, 32, v4
	v_and_b32_e32 v2, 0x100, v2
	s_addc_u32 s17, s10, s17
	v_or3_b32 v26, v5, v6, v7
	v_or3_b32 v63, v3, v4, v2
	s_add_i32 s15, s15, 0x1800000
	global_load_dwordx4 v[2:5], v98, s[16:17]
	s_mul_hi_i32 s1, s0, 0x600
	s_add_u32 s0, s2, s15
	v_add_u32_e32 v168, 0x8000, v98
	s_addc_u32 s1, s8, s1
	global_load_dwordx4 v[6:9], v168, s[16:17]
	global_load_dwordx4 v[10:13], v162, s[0:1]
	global_load_dwordx4 v[16:19], v164, s[0:1]
	global_load_dwordx4 v[20:23], v166, s[0:1]
	v_add_u32_e32 v178, 0, v26
	s_waitcnt vmcnt(0)
	v_add_u32_e32 v179, 0, v27
	v_add_u32_e32 v180, 0, v15
	v_add_u32_e32 v181, 0, v24
	v_add_u32_e32 v182, 0, v25
	s_movk_i32 s0, 0x70
	v_bitop3_b32 v61, v62, v14, s0 bitop3:0x78
	s_movk_i32 s0, 0x80
	v_add_u32_e32 v192, v51, v61
	v_add_u32_e32 v174, s14, v63
	s_mov_b32 s11, -1
	s_waitcnt vmcnt(4)
	ds_write_b128 v178, v[2:5]
	v_mov_b32_e32 v2, 0x3000
	v_mad_u32_u24 v60, v172, s18, v2
	v_bitop3_b32 v2, v62, v55, v50 bitop3:0xde
	v_add_u32_e32 v183, 0, v2
	s_waitcnt vmcnt(3)
	ds_write_b128 v179, v[6:9]
	s_waitcnt vmcnt(2)
	ds_write_b128 v180, v[10:13] offset:32768
	s_waitcnt vmcnt(1)
	ds_write_b128 v181, v[16:19] offset:32768
	s_waitcnt vmcnt(0)
	ds_write_b128 v182, v[20:23] offset:32768
	s_waitcnt lgkmcnt(0)
	s_barrier
	ds_read_b128 v[18:21], v183 offset:32768
	ds_read_b128 v[22:25], v183 offset:45056
	ds_read_b128 v[56:59], v184 offset:32768
	ds_read_b128 v[68:71], v184 offset:45056
	s_waitcnt lgkmcnt(3)
	v_mfma_f32_32x32x16_bf16 v[34:49], v[18:21], v[128:131], 0
	v_bitop3_b32 v66, v52, v60, v50 bitop3:0xde
	v_bitop3_b32 v52, v53, v55, v50 bitop3:0xde
	v_add_u32_e32 v185, 0, v52
	v_bitop3_b32 v52, v54, v55, v50 bitop3:0xde
	v_add_u32_e32 v186, 0, v52
	v_bitop3_b32 v67, v53, v60, v50 bitop3:0xde
	v_mov_b64_e32 v[2:3], s[68:69]
	s_waitcnt lgkmcnt(2)
	v_mfma_f32_32x32x16_bf16 v[18:33], v[22:25], v[128:131], 0
	v_mov_b64_e32 v[4:5], s[70:71]
	v_mov_b64_e32 v[6:7], s[72:73]
	v_mov_b64_e32 v[8:9], s[74:75]
	v_mov_b64_e32 v[10:11], s[76:77]
	v_mov_b64_e32 v[12:13], s[78:79]
	v_mov_b64_e32 v[14:15], s[80:81]
	v_mov_b64_e32 v[16:17], s[82:83]
	s_waitcnt lgkmcnt(1)
	v_mfma_f32_32x32x16_bf16 v[34:49], v[56:59], v[124:127], v[34:49]
	ds_read_b128 v[56:59], v185 offset:32768
	s_movk_i32 s82, 0x100
	ds_read_b128 v[74:77], v192
	v_bitop3_b32 v65, v62, v60, v50 bitop3:0xde
	v_readlane_b32 s80, v254, 41
	v_readlane_b32 s74, v254, 44
	v_readlane_b32 s81, v254, 42
	s_waitcnt lgkmcnt(2)
	v_mfma_f32_32x32x16_bf16 v[18:33], v[68:71], v[124:127], v[18:33]
	ds_read_b128 v[68:71], v185 offset:45056
	v_add_u32_e32 v226, 0, v65
	v_readlane_b32 s75, v254, 45
	v_readlane_b32 s83, v254, 43
	s_movk_i32 s81, 0x300
	v_add_u32_e32 v225, 0, v66
	v_add_u32_e32 v224, 0, v67
	s_waitcnt lgkmcnt(2)
	v_mfma_f32_32x32x16_bf16 v[34:49], v[56:59], v[120:123], v[34:49]
	ds_read_b128 v[56:59], v186 offset:32768
	s_waitcnt lgkmcnt(1)
	v_mfma_f32_32x32x16_bf16 v[18:33], v[68:71], v[120:123], v[18:33]
	v_bitop3_b32 v68, v54, v60, v50 bitop3:0xde
	ds_read_b128 v[52:55], v186 offset:45056
	v_add_u32_e32 v223, 0, v68
	s_waitcnt lgkmcnt(1)
	v_mfma_f32_32x32x16_bf16 v[34:49], v[56:59], v[116:119], v[34:49]
	v_bitop3_b32 v56, v62, v50, s0 bitop3:0x36
	v_add_u32_e32 v69, v56, v60
	s_movk_i32 s0, 0xa0
	v_add_u32_e32 v222, 0, v69
	s_waitcnt lgkmcnt(0)
	v_mfma_f32_32x32x16_bf16 v[18:33], v[52:55], v[116:119], v[18:33]
	v_mad_u32_u24 v52, v172, s18, v56
	v_add_u32_e32 v187, 0, v52
	ds_read_b128 v[52:55], v187 offset:32768
	ds_read_b128 v[56:59], v187 offset:45056
	s_waitcnt lgkmcnt(0)
	v_mfma_f32_32x32x16_bf16 v[18:33], v[56:59], v[112:115], v[18:33]
	v_bitop3_b32 v56, v62, v50, s0 bitop3:0x36
	v_add_u32_e32 v70, v56, v60
	s_movk_i32 s0, 0xc0
	v_add_u32_e32 v221, 0, v70
	v_mfma_f32_32x32x16_bf16 v[34:49], v[52:55], v[112:115], v[34:49]
	v_mad_u32_u24 v52, v172, s18, v56
	v_add_u32_e32 v188, 0, v52
	ds_read_b128 v[52:55], v188 offset:32768
	ds_read_b128 v[56:59], v188 offset:45056
	s_waitcnt lgkmcnt(0)
	v_mfma_f32_32x32x16_bf16 v[18:33], v[56:59], v[108:111], v[18:33]
	v_bitop3_b32 v56, v62, v50, s0 bitop3:0x36
	v_add_u32_e32 v71, v56, v60
	s_movk_i32 s0, 0xe0
	v_add_u32_e32 v220, 0, v71
	v_mfma_f32_32x32x16_bf16 v[34:49], v[52:55], v[108:111], v[34:49]
	v_mad_u32_u24 v52, v172, s18, v56
	v_add_u32_e32 v189, 0, v52
	ds_read_b128 v[52:55], v189 offset:32768
	ds_read_b128 v[56:59], v189 offset:45056
	s_waitcnt lgkmcnt(0)
	v_mfma_f32_32x32x16_bf16 v[18:33], v[56:59], v[104:107], v[18:33]
	v_bitop3_b32 v56, v62, v50, s0 bitop3:0x36
	v_add_u32_e32 v72, v56, v60
	s_movk_i32 s0, 0x120
	v_bitop3_b32 v51, v62, v50, s0 bitop3:0x36
	s_movk_i32 s0, 0x140
	v_add_u32_e32 v219, 0, v72
	v_mfma_f32_32x32x16_bf16 v[34:49], v[52:55], v[104:107], v[34:49]
	v_mad_u32_u24 v52, v172, s18, v56
	v_add_u32_e32 v190, 0, v52
	ds_read_b128 v[52:55], v190 offset:32768
	ds_read_b128 v[56:59], v190 offset:45056
	s_waitcnt lgkmcnt(0)
	v_mfma_f32_32x32x16_bf16 v[18:33], v[56:59], v[100:103], v[18:33]
	v_bitop3_b32 v56, v62, v50, s82 bitop3:0x36
	v_add_u32_e32 v73, v56, v60
	v_add_u32_e32 v218, 0, v73
	v_mfma_f32_32x32x16_bf16 v[34:49], v[52:55], v[100:103], v[34:49]
	v_mad_u32_u24 v52, v172, s18, v56
	v_add_u32_e32 v191, 0, v52
	ds_read_b128 v[52:55], v191 offset:32768
	ds_read_b128 v[56:59], v191 offset:45056
	s_waitcnt lgkmcnt(1)
	v_mfma_f32_32x32x16_bf16 v[34:49], v[52:55], v[74:77], v[34:49]
	v_mad_u32_u24 v52, v172, s18, v51
	v_add_u32_e32 v194, 0, v52
	ds_read_b128 v[52:55], v194 offset:32768
	s_waitcnt lgkmcnt(1)
	v_mfma_f32_32x32x16_bf16 v[18:33], v[56:59], v[74:77], v[18:33]
	ds_read_b128 v[56:59], v194 offset:45056
	ds_read_b128 v[76:79], v176
	v_add_u32_e32 v74, v51, v60
	v_bitop3_b32 v51, v62, v50, s0 bitop3:0x36
	s_movk_i32 s0, 0x160
	v_bitop3_b32 v50, v62, v50, s0 bitop3:0x36
	v_add_u32_e32 v75, v51, v60
	v_add_u32_e32 v217, 0, v74
	s_waitcnt lgkmcnt(0)
	v_mfma_f32_32x32x16_bf16 v[34:49], v[52:55], v[76:79], v[34:49]
	v_mad_u32_u24 v52, v172, s18, v51
	v_add_u32_e32 v195, 0, v52
	ds_read_b128 v[52:55], v195 offset:32768
	v_mad_u32_u24 v51, v172, s18, v50
	v_add_u32_e32 v196, 0, v51
	v_add_u32_e32 v216, 0, v75
	v_mfma_f32_32x32x16_bf16 v[18:33], v[56:59], v[76:79], v[18:33]
	ds_read_b128 v[56:59], v195 offset:45056
	ds_read_b128 v[76:79], v177
	s_waitcnt lgkmcnt(0)
	v_mfma_f32_32x32x16_bf16 v[34:49], v[52:55], v[76:79], v[34:49]
	v_mfma_f32_32x32x16_bf16 v[18:33], v[56:59], v[76:79], v[18:33]
	ds_read_b128 v[54:57], v196 offset:32768
	v_add_u32_e32 v76, v50, v60
	ds_read_b128 v[50:53], v196 offset:45056
	ds_read_b128 v[58:61], v175
	v_add_u32_e32 v215, 0, v76
	s_waitcnt lgkmcnt(0)
	v_mfma_f32_32x32x16_bf16 v[34:49], v[54:57], v[58:61], v[34:49]
	v_mfma_f32_32x32x16_bf16 v[18:33], v[50:53], v[58:61], v[18:33]
	s_nop 10
	v_max_f32_e32 v50, v35, v35
	v_max_f32_e32 v51, v34, v34
	v_max_f32_e32 v50, v51, v50
	v_max3_f32 v50, v50, v36, v37
	v_max3_f32 v50, v50, v38, v39
	v_max3_f32 v50, v50, v40, v41
	v_max3_f32 v50, v50, v42, v43
	v_max3_f32 v50, v50, v44, v45
	v_max3_f32 v50, v50, v46, v47
	v_max3_f32 v50, v50, v48, v49
	v_max3_f32 v50, v50, v18, v19
	v_max3_f32 v50, v50, v20, v21
	v_max3_f32 v50, v50, v22, v23
	v_max3_f32 v50, v50, v24, v25
	v_max3_f32 v50, v50, v26, v27
	v_max3_f32 v50, v50, v28, v29
	v_max3_f32 v50, v50, v30, v31
	v_max3_f32 v50, v50, v32, v33
	v_mov_b32_e32 v51, v50
	s_nop 1
	v_permlane32_swap_b32_e32 v50, v51
	v_max_f32_e32 v51, v51, v51
	v_max_f32_e32 v50, v50, v50
	v_max_f32_e32 v50, v50, v51
	v_add_f32_e32 v51, 0x7149f2ca, v50
	v_max_f32_e32 v50, 0xf149f2ca, v50
	v_cmp_ge_f32_e32 vcc, s5, v51
	v_sub_f32_e32 v51, 0xf149f2ca, v50
	s_cmp_eq_u64 vcc, exec
	v_mul_f32_e32 v51, 0x3dd53b94, v51
	s_cselect_b64 vcc, -1, 0
	v_exp_f32_e32 v51, v51
	s_add_i32 s0, s12, 0x4040
	v_mov_b32_e32 v52, 0xf149f2ca
	s_ashr_i32 s1, s0, 31
	v_cndmask_b32_e32 v214, v50, v52, vcc
	s_lshl_b64 s[16:17], s[0:1], 10
	v_mul_f32_e32 v50, 0xbdd53b94, v214
	s_add_u32 s16, s9, s16
	v_cndmask_b32_e64 v213, v51, 1.0, vcc
	v_mov_b32_e32 v51, v50
	s_addc_u32 s17, s10, s17
	s_mul_hi_i32 s1, s0, 0x600
	s_mulk_i32 s0, 0x600
	v_fmamk_f32 v34, v34, 0x3dd53b94, v50
	v_fmamk_f32 v35, v35, 0x3dd53b94, v50
	v_fmamk_f32 v36, v36, 0x3dd53b94, v50
	v_fmamk_f32 v37, v37, 0x3dd53b94, v50
	v_fmac_f32_e32 v51, 0x3dd53b94, v49
	s_add_u32 s0, s2, s0
	v_pk_fma_f32 v[138:139], v[32:33], s[30:31], v[50:51] op_sel_hi:[1,0,0]
	v_pk_fma_f32 v[140:141], v[30:31], s[30:31], v[50:51] op_sel_hi:[1,0,0]
	v_pk_fma_f32 v[146:147], v[28:29], s[30:31], v[50:51] op_sel_hi:[1,0,0]
	v_pk_fma_f32 v[132:133], v[26:27], s[30:31], v[50:51] op_sel_hi:[1,0,0]
	v_pk_fma_f32 v[134:135], v[24:25], s[30:31], v[50:51] op_sel_hi:[1,0,0]
	v_pk_fma_f32 v[136:137], v[22:23], s[30:31], v[50:51] op_sel_hi:[1,0,0]
	v_pk_fma_f32 v[142:143], v[20:21], s[30:31], v[50:51] op_sel_hi:[1,0,0]
	v_pk_fma_f32 v[144:145], v[18:19], s[30:31], v[50:51] op_sel_hi:[1,0,0]
	v_exp_f32_e32 v153, v34
	v_exp_f32_e32 v154, v35
	v_exp_f32_e32 v230, v36
	v_exp_f32_e32 v231, v37
	s_addc_u32 s1, s8, s1
	global_load_dwordx4 v[18:21], v98, s[16:17]
	global_load_dwordx4 v[22:25], v168, s[16:17]
	global_load_dwordx4 v[26:29], v162, s[0:1]
	global_load_dwordx4 v[30:33], v164, s[0:1]
	global_load_dwordx4 v[34:37], v166, s[0:1]
	v_fmamk_f32 v38, v38, 0x3dd53b94, v50
	v_fmamk_f32 v39, v39, 0x3dd53b94, v50
	v_fmamk_f32 v40, v40, 0x3dd53b94, v50
	v_fmamk_f32 v41, v41, 0x3dd53b94, v50
	v_fmamk_f32 v42, v42, 0x3dd53b94, v50
	v_fmamk_f32 v43, v43, 0x3dd53b94, v50
	v_fmamk_f32 v44, v44, 0x3dd53b94, v50
	v_fmamk_f32 v45, v45, 0x3dd53b94, v50
	v_fmamk_f32 v46, v46, 0x3dd53b94, v50
	v_fmamk_f32 v47, v47, 0x3dd53b94, v50
	v_fmamk_f32 v48, v48, 0x3dd53b94, v50
	v_exp_f32_e32 v232, v38
	v_exp_f32_e32 v233, v39
	v_exp_f32_e32 v155, v40
	v_exp_f32_e32 v229, v41
	v_exp_f32_e32 v151, v42
	v_exp_f32_e32 v156, v43
	v_exp_f32_e32 v157, v44
	v_exp_f32_e32 v158, v45
	v_exp_f32_e32 v148, v46
	v_exp_f32_e32 v149, v47
	v_exp_f32_e32 v150, v48
	v_exp_f32_e32 v159, v51
	s_waitcnt vmcnt(0)
	s_addk_i32 s14, 0x4000
	s_waitcnt vmcnt(4)
	ds_write_b128 v178, v[18:21] offset:16384
	s_waitcnt vmcnt(3)
	ds_write_b128 v179, v[22:25] offset:16384
	s_waitcnt vmcnt(2)
	ds_write_b128 v180, v[26:29] offset:57344
	s_waitcnt vmcnt(1)
	ds_write_b128 v181, v[30:33] offset:57344
	s_waitcnt vmcnt(0)
	ds_write_b128 v182, v[34:37] offset:57344
	s_mov_b32 s100, 0xaaaaaaab
	v_lshrrev_b32_e32 v38, 6, v0
	v_lshl_add_u32 v39, v38, 7, v0
	v_mul_hi_u32 v40, v39, s100
	v_lshrrev_b32_e32 v40, 4, v40
	v_mul_u32_u24_e32 v41, 24, v40
	v_sub_u32_e32 v41, v39, v41
	v_and_b32_e32 v42, 7, v40
	v_xor_b32_e32 v41, v41, v42
	v_mul_u32_u24_e32 v42, 0x600, v40
	v_lshl_add_u32 v180, v41, 4, v42
	v_add_u32_e32 v39, 64, v39
	v_mul_hi_u32 v40, v39, s100
	v_lshrrev_b32_e32 v40, 4, v40
	v_mul_u32_u24_e32 v41, 24, v40
	v_sub_u32_e32 v41, v39, v41
	v_and_b32_e32 v42, 7, v40
	v_xor_b32_e32 v41, v41, v42
	v_mul_u32_u24_e32 v42, 0x600, v40
	v_lshl_add_u32 v181, v41, 4, v42
	v_add_u32_e32 v39, 64, v39
	v_mul_hi_u32 v40, v39, s100
	v_lshrrev_b32_e32 v40, 4, v40
	v_mul_u32_u24_e32 v41, 24, v40
	v_sub_u32_e32 v41, v39, v41
	v_and_b32_e32 v42, 7, v40
	v_xor_b32_e32 v41, v41, v42
	v_mul_u32_u24_e32 v42, 0x600, v40
	v_lshl_add_u32 v182, v41, 4, v42
	v_lshl_add_u32 v39, v38, 6, v0
	v_and_b32_e32 v40, 3, v39
	v_lshlrev_b32_e32 v40, 4, v40
	v_bfe_u32 v41, v39, 5, 2
	v_lshl_or_b32 v40, v41, 6, v40
	v_bfe_u32 v41, v39, 2, 2
	v_lshl_or_b32 v40, v41, 10, v40
	v_bfe_u32 v41, v39, 7, 1
	v_lshl_or_b32 v40, v41, 12, v40
	v_bfe_u32 v41, v39, 4, 1
	v_lshl_or_b32 v40, v41, 13, v40
	v_bfe_u32 v41, v39, 8, 2
	v_lshl_or_b32 v178, v41, 14, v40
	v_add_u32_e32 v39, 64, v39
	v_and_b32_e32 v40, 3, v39
	v_lshlrev_b32_e32 v40, 4, v40
	v_bfe_u32 v41, v39, 5, 2
	v_lshl_or_b32 v40, v41, 6, v40
	v_bfe_u32 v41, v39, 2, 2
	v_lshl_or_b32 v40, v41, 10, v40
	v_bfe_u32 v41, v39, 7, 1
	v_lshl_or_b32 v40, v41, 12, v40
	v_bfe_u32 v41, v39, 4, 1
	v_lshl_or_b32 v40, v41, 13, v40
	v_bfe_u32 v41, v39, 8, 2
	v_lshl_or_b32 v179, v41, 14, v40
	v_readfirstlane_b32 s100, v38
	s_nop 1
	s_mul_i32 s101, s100, 0xc00
	s_lshl_b32 s100, s100, 11
	v_add_u32_e32 v199, s14, v63
	v_mov_b64_e32 v[64:65], v[16:17]
	v_mov_b64_e32 v[48:49], v[16:17]
	v_mov_b64_e32 v[32:33], v[16:17]
	s_addk_i32 s12, 0x4080
	s_sub_i32 s13, s13, 64
	v_mov_b64_e32 v[62:63], v[14:15]
	v_mov_b64_e32 v[60:61], v[12:13]
	v_mov_b64_e32 v[58:59], v[10:11]
	v_mov_b64_e32 v[56:57], v[8:9]
	v_mov_b64_e32 v[54:55], v[6:7]
	v_mov_b64_e32 v[52:53], v[4:5]
	v_mov_b64_e32 v[50:51], v[2:3]
	v_mov_b64_e32 v[46:47], v[14:15]
	v_mov_b64_e32 v[44:45], v[12:13]
	v_mov_b64_e32 v[42:43], v[10:11]
	v_mov_b64_e32 v[40:41], v[8:9]
	v_mov_b64_e32 v[38:39], v[6:7]
	v_mov_b64_e32 v[36:37], v[4:5]
	v_mov_b64_e32 v[34:35], v[2:3]
	v_mov_b64_e32 v[30:31], v[14:15]
	v_mov_b64_e32 v[28:29], v[12:13]
	v_mov_b64_e32 v[26:27], v[10:11]
	v_mov_b64_e32 v[24:25], v[8:9]
	v_mov_b64_e32 v[22:23], v[6:7]
	v_mov_b64_e32 v[20:21], v[4:5]
	v_mov_b64_e32 v[18:19], v[2:3]
	s_mov_b32 s14, s16
	s_mov_b32 s15, s17
	s_waitcnt lgkmcnt(0)
	s_barrier
.LBB0_855:
	s_add_i32 s11, s11, 2
	s_add_i32 m0, s100, 0x4000
	s_nop 0
	global_load_lds_dwordx4 v178, s[14:15]
	s_add_i32 m0, s100, 0x4400
	s_nop 0
	global_load_lds_dwordx4 v179, s[14:15]
	s_sub_i32 s0, s13, 64
	s_cmp_lt_u32 s11, 3
	s_cselect_b32 s0, s12, s0
	s_ashr_i32 s1, s0, 31
	s_lshl_b64 s[14:15], s[0:1], 10
	s_add_u32 s14, s9, s14
	s_addc_u32 s15, s10, s15
	s_mul_hi_i32 s1, s0, 0x600
	s_mulk_i32 s0, 0x600
	s_add_u32 s0, s2, s0
	s_addc_u32 s1, s8, s1
	s_add_i32 m0, s101, 0x8000
	s_nop 0
	global_load_lds_dwordx4 v180, s[0:1]
	s_add_i32 m0, s101, 0x8400
	s_nop 0
	global_load_lds_dwordx4 v181, s[0:1]
	s_add_i32 m0, s101, 0x8800
	s_nop 0
	global_load_lds_dwordx4 v182, s[0:1]
	ds_read_b128 v[66:69], v183 offset:57344
	ds_read_b128 v[70:73], v226 offset:57344
	ds_read_b128 v[234:237], v184 offset:57344
	ds_read_b128 v[238:241], v225 offset:57344
	v_add_f32_e32 v152, 0, v153
	v_add_f32_e32 v152, v154, v152
	s_waitcnt lgkmcnt(2)
	v_mfma_f32_32x32x16_bf16 v[82:97], v[66:69], v[128:131], 0
	v_add_f32_e32 v152, v230, v152
	v_add_f32_e32 v152, v231, v152
	v_add_f32_e32 v152, v232, v152
	v_add_f32_e32 v152, v233, v152
	v_add_f32_e32 v152, v155, v152
	v_add_f32_e32 v152, v229, v152
	v_add_f32_e32 v152, v151, v152
	v_mfma_f32_32x32x16_bf16 v[66:81], v[70:73], v[128:131], 0
	ds_read_b128 v[162:165], v185 offset:57344
	ds_read_b128 v[166:169], v224 offset:57344
	v_add_f32_e32 v152, v156, v152
	v_add_f32_e32 v152, v157, v152
	v_add_f32_e32 v152, v158, v152
	v_exp_f32_e32 v144, v144
	v_add_f32_e32 v152, v148, v152
	v_exp_f32_e32 v145, v145
	v_add_f32_e32 v152, v149, v152
	s_waitcnt lgkmcnt(2)
	v_mfma_f32_32x32x16_bf16 v[82:97], v[234:237], v[124:127], v[82:97]
	v_exp_f32_e32 v142, v142
	v_add_f32_e32 v152, v150, v152
	v_exp_f32_e32 v143, v143
	v_add_f32_e32 v152, v159, v152
	v_exp_f32_e32 v136, v136
	v_add_f32_e32 v152, v144, v152
	v_exp_f32_e32 v137, v137
	v_mfma_f32_32x32x16_bf16 v[66:81], v[238:241], v[124:127], v[66:81]
	ds_read_b128 v[234:237], v186 offset:57344
	ds_read_b128 v[238:241], v223 offset:57344
	v_add_f32_e32 v152, v145, v152
	v_exp_f32_e32 v134, v134
	v_add_f32_e32 v152, v142, v152
	v_exp_f32_e32 v135, v135
	v_add_f32_e32 v152, v143, v152
	v_exp_f32_e32 v132, v132
	s_waitcnt lgkmcnt(2)
	v_mfma_f32_32x32x16_bf16 v[82:97], v[162:165], v[120:123], v[82:97]
	v_add_f32_e32 v152, v136, v152
	v_exp_f32_e32 v133, v133
	v_add_f32_e32 v152, v137, v152
	v_exp_f32_e32 v146, v146
	v_add_f32_e32 v152, v134, v152
	v_exp_f32_e32 v147, v147
	v_add_f32_e32 v152, v135, v152
	v_mfma_f32_32x32x16_bf16 v[66:81], v[166:169], v[120:123], v[66:81]
	ds_read_b128 v[162:165], v187 offset:57344
	ds_read_b128 v[166:169], v222 offset:57344
	v_exp_f32_e32 v140, v140
	v_add_f32_e32 v152, v132, v152
	v_exp_f32_e32 v141, v141
	v_add_f32_e32 v152, v133, v152
	v_exp_f32_e32 v138, v138
	v_add_f32_e32 v152, v146, v152
	s_waitcnt lgkmcnt(2)
	v_mfma_f32_32x32x16_bf16 v[82:97], v[234:237], v[116:119], v[82:97]
	v_exp_f32_e32 v139, v139
	v_add_f32_e32 v152, v147, v152
	v_add_f32_e32 v152, v140, v152
	v_add_f32_e32 v152, v141, v152
	v_add_f32_e32 v152, v138, v152
	v_add_f32_e32 v227, v139, v152
	v_mov_b32_e32 v228, v227
	v_mfma_f32_32x32x16_bf16 v[66:81], v[238:241], v[116:119], v[66:81]
	ds_read_b128 v[234:237], v188 offset:57344
	ds_read_b128 v[238:241], v221 offset:57344
	v_cvt_pk_bf16_f32 v152, v153, v154
	v_cvt_pk_bf16_f32 v154, v232, v233
	v_permlane32_swap_b32_e32 v227, v228
	v_cvt_pk_bf16_f32 v153, v230, v231
	v_cvt_pk_bf16_f32 v155, v155, v229
	s_waitcnt lgkmcnt(2)
	v_mfma_f32_32x32x16_bf16 v[82:97], v[162:165], v[112:115], v[82:97]
	v_permlane32_swap_b32_e32 v152, v154
	v_cvt_pk_bf16_f32 v156, v151, v156
	v_cvt_pk_bf16_f32 v157, v157, v158
	v_cvt_pk_bf16_f32 v158, v148, v149
	v_cvt_pk_bf16_f32 v159, v150, v159
	v_cvt_pk_bf16_f32 v230, v144, v145
	v_mfma_f32_32x32x16_bf16 v[66:81], v[166:169], v[112:115], v[66:81]
	ds_read_b128 v[162:165], v189 offset:57344
	ds_read_b128 v[166:169], v220 offset:57344
	v_cvt_pk_bf16_f32 v231, v142, v143
	v_cvt_pk_bf16_f32 v232, v136, v137
	v_cvt_pk_bf16_f32 v233, v134, v135
	v_permlane32_swap_b32_e32 v153, v155
	v_permlane32_swap_b32_e32 v156, v158
	s_waitcnt lgkmcnt(2)
	v_mfma_f32_32x32x16_bf16 v[82:97], v[234:237], v[108:111], v[82:97]
	v_permlane32_swap_b32_e32 v157, v159
	v_permlane32_swap_b32_e32 v230, v232
	v_permlane32_swap_b32_e32 v231, v233
	v_mfma_f32_32x32x16_bf16 v[66:81], v[238:241], v[108:111], v[66:81]
	ds_read_b128 v[234:237], v190 offset:57344
	ds_read_b128 v[238:241], v219 offset:57344
	s_waitcnt lgkmcnt(2)
	v_mfma_f32_32x32x16_bf16 v[82:97], v[162:165], v[104:107], v[82:97]
	v_mfma_f32_32x32x16_bf16 v[66:81], v[166:169], v[104:107], v[66:81]
	ds_read_b128 v[162:165], v191 offset:57344
	ds_read_b128 v[166:169], v218 offset:57344
	ds_read_b128 v[242:245], v192
	s_waitcnt lgkmcnt(3)
	v_mfma_f32_32x32x16_bf16 v[82:97], v[234:237], v[100:103], v[82:97]
	v_mfma_f32_32x32x16_bf16 v[66:81], v[238:241], v[100:103], v[66:81]
	ds_read_b128 v[234:237], v194 offset:57344
	ds_read_b128 v[238:241], v217 offset:57344
	ds_read_b128 v[246:249], v176
	s_waitcnt lgkmcnt(3)
	v_mfma_f32_32x32x16_bf16 v[82:97], v[162:165], v[242:245], v[82:97]
	v_mfma_f32_32x32x16_bf16 v[66:81], v[166:169], v[242:245], v[66:81]
	ds_read_b128 v[162:165], v195 offset:57344
	ds_read_b128 v[166:169], v216 offset:57344
	ds_read_b128 v[242:245], v177
	s_waitcnt lgkmcnt(3)
	v_mfma_f32_32x32x16_bf16 v[82:97], v[234:237], v[246:249], v[82:97]
	v_mfma_f32_32x32x16_bf16 v[66:81], v[238:241], v[246:249], v[66:81]
	ds_read_b128 v[234:237], v196 offset:57344
	ds_read_b128 v[238:241], v215 offset:57344
	ds_read_b128 v[246:249], v175
	s_waitcnt lgkmcnt(3)
	v_mfma_f32_32x32x16_bf16 v[82:97], v[162:165], v[242:245], v[82:97]
	v_mfma_f32_32x32x16_bf16 v[66:81], v[166:169], v[242:245], v[66:81]
	s_waitcnt lgkmcnt(0)
	v_mfma_f32_32x32x16_bf16 v[82:97], v[234:237], v[246:249], v[82:97]
	v_cvt_pk_bf16_f32 v234, v132, v133
	v_cvt_pk_bf16_f32 v236, v140, v141
	v_cvt_pk_bf16_f32 v235, v146, v147
	v_cvt_pk_bf16_f32 v237, v138, v139
	v_permlane32_swap_b32_e32 v234, v236
	s_nop 0
	v_permlane32_swap_b32_e32 v235, v237
	v_mfma_f32_32x32x16_bf16 v[66:81], v[238:241], v[246:249], v[66:81]
	ds_read_b64_tr_b16 v[238:239], v174 offset:0
	ds_read_b64_tr_b16 v[240:241], v174 offset:0x800
	ds_read_b64_tr_b16 v[242:243], v174 offset:0x1000
	ds_read_b64_tr_b16 v[244:245], v174 offset:0x1800
	ds_read_b64_tr_b16 v[246:247], v174 offset:0x2000
	ds_read_b64_tr_b16 v[248:249], v174 offset:0x2800
	ds_read_b64_tr_b16 v[204:205], v174 offset:0x3000
	ds_read_b64_tr_b16 v[206:207], v174 offset:0x3800
	s_nop 0
	s_waitcnt lgkmcnt(6)
	v_mfma_f32_32x32x16_bf16 v[2:17], v[152:155], v[238:241], v[2:17]
	s_waitcnt lgkmcnt(4)
	v_mfma_f32_32x32x16_bf16 v[2:17], v[156:159], v[242:245], v[2:17]
	s_waitcnt lgkmcnt(2)
	v_mfma_f32_32x32x16_bf16 v[2:17], v[230:233], v[246:249], v[2:17]
	s_waitcnt lgkmcnt(0)
	v_mfma_f32_32x32x16_bf16 v[2:17], v[234:237], v[204:207], v[2:17]
	ds_read_b64_tr_b16 v[204:205], v174 offset:0x200
	ds_read_b64_tr_b16 v[206:207], v174 offset:0xa00
	ds_read_b64_tr_b16 v[238:239], v174 offset:0x1200
	ds_read_b64_tr_b16 v[240:241], v174 offset:0x1a00
	ds_read_b64_tr_b16 v[242:243], v174 offset:0x2200
	ds_read_b64_tr_b16 v[244:245], v174 offset:0x2a00
	ds_read_b64_tr_b16 v[246:247], v174 offset:0x3200
	ds_read_b64_tr_b16 v[248:249], v174 offset:0x3a00
	s_nop 0
	s_waitcnt lgkmcnt(6)
	v_mfma_f32_32x32x16_bf16 v[50:65], v[152:155], v[204:207], v[50:65]
	ds_read_b64_tr_b16 v[204:205], v174 offset:0x400
	ds_read_b64_tr_b16 v[206:207], v174 offset:0xc00
	s_waitcnt lgkmcnt(6)
	v_mfma_f32_32x32x16_bf16 v[50:65], v[156:159], v[238:241], v[50:65]
	ds_read_b64_tr_b16 v[238:239], v174 offset:0x1400
	ds_read_b64_tr_b16 v[240:241], v174 offset:0x1c00
	s_waitcnt lgkmcnt(6)
	v_mfma_f32_32x32x16_bf16 v[50:65], v[230:233], v[242:245], v[50:65]
	ds_read_b64_tr_b16 v[242:243], v174 offset:0x2400
	ds_read_b64_tr_b16 v[244:245], v174 offset:0x2c00
	s_waitcnt lgkmcnt(6)
	v_mfma_f32_32x32x16_bf16 v[50:65], v[234:237], v[246:249], v[50:65]
	ds_read_b64_tr_b16 v[246:247], v174 offset:0x3400
	ds_read_b64_tr_b16 v[248:249], v174 offset:0x3c00
	s_waitcnt lgkmcnt(6)
	v_mfma_f32_32x32x16_bf16 v[34:49], v[152:155], v[204:207], v[34:49]
	ds_read_b64_tr_b16 v[204:205], v174 offset:0x600
	ds_read_b64_tr_b16 v[206:207], v174 offset:0xe00
	s_waitcnt lgkmcnt(6)
	v_mfma_f32_32x32x16_bf16 v[34:49], v[156:159], v[238:241], v[34:49]
	ds_read_b64_tr_b16 v[238:239], v174 offset:0x1600
	ds_read_b64_tr_b16 v[240:241], v174 offset:0x1e00
	s_waitcnt lgkmcnt(6)
	v_mfma_f32_32x32x16_bf16 v[34:49], v[230:233], v[242:245], v[34:49]
	ds_read_b64_tr_b16 v[242:243], v174 offset:0x2600
	ds_read_b64_tr_b16 v[244:245], v174 offset:0x2e00
	s_waitcnt lgkmcnt(6)
	v_mfma_f32_32x32x16_bf16 v[34:49], v[234:237], v[246:249], v[34:49]
	ds_read_b64_tr_b16 v[246:247], v174 offset:0x3600
	ds_read_b64_tr_b16 v[248:249], v174 offset:0x3e00
	s_waitcnt lgkmcnt(6)
	v_mfma_f32_32x32x16_bf16 v[18:33], v[152:155], v[204:207], v[18:33]
	v_max_f32_e32 v152, v83, v83
	v_max_f32_e32 v153, v82, v82
	v_max_f32_e32 v152, v153, v152
	v_max3_f32 v152, v152, v84, v85
	v_max3_f32 v152, v152, v86, v87
	v_max3_f32 v152, v152, v88, v89
	v_max3_f32 v152, v152, v90, v91
	v_max3_f32 v152, v152, v92, v93
	v_max3_f32 v152, v152, v94, v95
	s_waitcnt lgkmcnt(4)
	v_mfma_f32_32x32x16_bf16 v[18:33], v[156:159], v[238:241], v[18:33]
	v_max3_f32 v152, v152, v96, v97
	v_max3_f32 v152, v152, v66, v67
	v_max3_f32 v152, v152, v68, v69
	v_max3_f32 v152, v152, v70, v71
	v_max3_f32 v152, v152, v72, v73
	v_max3_f32 v152, v152, v74, v75
	v_max3_f32 v152, v152, v76, v77
	v_max3_f32 v152, v152, v78, v79
	s_waitcnt lgkmcnt(2)
	v_mfma_f32_32x32x16_bf16 v[18:33], v[230:233], v[242:245], v[18:33]
	v_max3_f32 v152, v152, v80, v81
	v_mov_b32_e32 v153, v152
	s_nop 1
	v_permlane32_swap_b32_e32 v152, v153
	v_max_f32_e32 v153, v153, v153
	v_max_f32_e32 v152, v152, v152
	v_max_f32_e32 v152, v152, v153
	v_sub_f32_e32 v153, v152, v214
	v_cmp_ge_f32_e32 vcc, s5, v153
	v_max_f32_e32 v153, v214, v214
	v_max_f32_e32 v152, v153, v152
	s_waitcnt lgkmcnt(0)
	v_mfma_f32_32x32x16_bf16 v[18:33], v[234:237], v[246:249], v[18:33]
	v_sub_f32_e32 v153, v214, v152
	v_mul_f32_e32 v153, 0x3dd53b94, v153
	v_exp_f32_e32 v153, v153
	s_cmp_eq_u64 vcc, exec
	s_cselect_b64 s[40:41], -1, 0
	v_cndmask_b32_e64 v234, v153, 1.0, s[40:41]
	s_nop 0
	v_cmp_gt_f32_e32 vcc, 1.0, v234
	s_cbranch_vccz .LBB0_859
	s_and_saveexec_b64 s[0:1], s[38:39]
	ds_write_b32 v197, v234 offset:128
	s_or_b64 exec, exec, s[0:1]
	s_waitcnt lgkmcnt(0)
	ds_read_b128 v[132:135], v193 offset:224
	ds_read_b128 v[136:139], v193 offset:192
	ds_read_b128 v[140:143], v193 offset:160
	ds_read_b128 v[144:147], v193 offset:128
	s_waitcnt lgkmcnt(3)
	v_pk_mul_f32 v[16:17], v[16:17], v[134:135]
	s_waitcnt lgkmcnt(2)
	v_pk_mul_f32 v[12:13], v[12:13], v[138:139]
	s_waitcnt lgkmcnt(1)
	v_pk_mul_f32 v[8:9], v[8:9], v[142:143]
	s_waitcnt lgkmcnt(0)
	v_pk_mul_f32 v[4:5], v[4:5], v[146:147]
	v_pk_mul_f32 v[14:15], v[14:15], v[132:133]
	v_pk_mul_f32 v[10:11], v[10:11], v[136:137]
	v_pk_mul_f32 v[6:7], v[6:7], v[140:141]
	v_pk_mul_f32 v[2:3], v[2:3], v[144:145]
	v_pk_mul_f32 v[64:65], v[64:65], v[134:135]
	v_pk_mul_f32 v[60:61], v[60:61], v[138:139]
	v_pk_mul_f32 v[56:57], v[56:57], v[142:143]
	v_pk_mul_f32 v[52:53], v[52:53], v[146:147]
	v_pk_mul_f32 v[62:63], v[62:63], v[132:133]
	v_pk_mul_f32 v[58:59], v[58:59], v[136:137]
	v_pk_mul_f32 v[54:55], v[54:55], v[140:141]
	v_pk_mul_f32 v[50:51], v[50:51], v[144:145]
	v_pk_mul_f32 v[48:49], v[48:49], v[134:135]
	v_pk_mul_f32 v[44:45], v[44:45], v[138:139]
	v_pk_mul_f32 v[40:41], v[40:41], v[142:143]
	v_pk_mul_f32 v[36:37], v[36:37], v[146:147]
	v_pk_mul_f32 v[46:47], v[46:47], v[132:133]
	v_pk_mul_f32 v[42:43], v[42:43], v[136:137]
	v_pk_mul_f32 v[38:39], v[38:39], v[140:141]
	v_pk_mul_f32 v[34:35], v[34:35], v[144:145]
	v_pk_mul_f32 v[32:33], v[32:33], v[134:135]
	v_pk_mul_f32 v[28:29], v[28:29], v[138:139]
	v_pk_mul_f32 v[24:25], v[24:25], v[142:143]
	v_pk_mul_f32 v[20:21], v[20:21], v[146:147]
	v_pk_mul_f32 v[30:31], v[30:31], v[132:133]
	v_pk_mul_f32 v[26:27], v[26:27], v[136:137]
	v_pk_mul_f32 v[22:23], v[22:23], v[140:141]
	v_pk_mul_f32 v[18:19], v[18:19], v[144:145]
.LBB0_859:
	v_cndmask_b32_e64 v214, v152, v214, s[40:41]
	v_mul_f32_e32 v148, 0xbdd53b94, v214
	v_fmamk_f32 v82, v82, 0x3dd53b94, v148
	v_fmamk_f32 v83, v83, 0x3dd53b94, v148
	v_fmamk_f32 v84, v84, 0x3dd53b94, v148
	v_fmamk_f32 v85, v85, 0x3dd53b94, v148
	v_fmamk_f32 v86, v86, 0x3dd53b94, v148
	v_fmamk_f32 v87, v87, 0x3dd53b94, v148
	v_fmamk_f32 v88, v88, 0x3dd53b94, v148
	v_fmamk_f32 v89, v89, 0x3dd53b94, v148
	v_fmamk_f32 v90, v90, 0x3dd53b94, v148
	v_fmamk_f32 v91, v91, 0x3dd53b94, v148
	v_fmamk_f32 v92, v92, 0x3dd53b94, v148
	v_fmamk_f32 v93, v93, 0x3dd53b94, v148
	v_fmamk_f32 v94, v94, 0x3dd53b94, v148
	v_fmamk_f32 v95, v95, 0x3dd53b94, v148
	v_fmamk_f32 v96, v96, 0x3dd53b94, v148
	v_fmamk_f32 v97, v97, 0x3dd53b94, v148
	v_fmamk_f32 v152, v73, 0x3dd53b94, v148
	v_fmamk_f32 v153, v74, 0x3dd53b94, v148
	v_fmamk_f32 v157, v66, 0x3dd53b94, v148
	v_fmamk_f32 v158, v67, 0x3dd53b94, v148
	v_fmamk_f32 v159, v68, 0x3dd53b94, v148
	v_fmamk_f32 v229, v69, 0x3dd53b94, v148
	v_fmamk_f32 v230, v70, 0x3dd53b94, v148
	v_fmamk_f32 v150, v71, 0x3dd53b94, v148
	v_fmamk_f32 v151, v72, 0x3dd53b94, v148
	v_fmamk_f32 v154, v75, 0x3dd53b94, v148
	v_fmamk_f32 v155, v76, 0x3dd53b94, v148
	v_fmamk_f32 v156, v77, 0x3dd53b94, v148
	v_fmamk_f32 v149, v78, 0x3dd53b94, v148
	v_exp_f32_e32 v141, v82
	v_exp_f32_e32 v143, v83
	v_exp_f32_e32 v144, v84
	v_exp_f32_e32 v145, v85
	v_exp_f32_e32 v146, v86
	v_exp_f32_e32 v147, v87
	v_exp_f32_e32 v140, v88
	v_exp_f32_e32 v142, v89
	v_exp_f32_e32 v135, v90
	v_exp_f32_e32 v137, v91
	v_exp_f32_e32 v138, v92
	v_exp_f32_e32 v139, v93
	v_exp_f32_e32 v132, v94
	v_exp_f32_e32 v133, v95
	v_exp_f32_e32 v134, v96
	v_exp_f32_e32 v136, v97
	v_fmamk_f32 v231, v79, 0x3dd53b94, v148
	v_fmamk_f32 v232, v80, 0x3dd53b94, v148
	v_fmac_f32_e32 v148, 0x3dd53b94, v81
	s_waitcnt vmcnt(0) lgkmcnt(0)
	s_barrier
	s_add_i32 m0, s100, 0x0
	s_nop 0
	global_load_lds_dwordx4 v178, s[14:15]
	s_add_i32 m0, s100, 0x400
	s_nop 0
	global_load_lds_dwordx4 v179, s[14:15]
	s_add_i32 s0, s12, 64
	s_cmp_lt_u32 s11, 2
	s_cselect_b32 s0, s0, s13
	s_ashr_i32 s1, s0, 31
	s_lshl_b64 s[14:15], s[0:1], 10
	s_add_u32 s14, s9, s14
	s_addc_u32 s15, s10, s15
	s_mul_hi_i32 s1, s0, 0x600
	s_mulk_i32 s0, 0x600
	s_add_u32 s0, s2, s0
	s_addc_u32 s1, s8, s1
	s_add_i32 m0, s101, 0xe000
	s_nop 0
	global_load_lds_dwordx4 v180, s[0:1]
	s_add_i32 m0, s101, 0xe400
	s_nop 0
	global_load_lds_dwordx4 v181, s[0:1]
	s_add_i32 m0, s101, 0xe800
	s_nop 0
	global_load_lds_dwordx4 v182, s[0:1]
	ds_read_b128 v[66:69], v183 offset:32768
	ds_read_b128 v[70:73], v183 offset:45056
	ds_read_b128 v[204:207], v184 offset:32768
	ds_read_b128 v[236:239], v184 offset:45056
	v_exp_f32_e32 v209, v152
	v_add_f32_e32 v152, 0, v141
	s_waitcnt lgkmcnt(2)
	v_mfma_f32_32x32x16_bf16 v[82:97], v[66:69], v[128:131], 0
	v_add_f32_e32 v152, v143, v152
	v_add_f32_e32 v152, v144, v152
	v_add_f32_e32 v152, v145, v152
	v_add_f32_e32 v152, v146, v152
	v_add_f32_e32 v152, v147, v152
	v_add_f32_e32 v152, v140, v152
	v_add_f32_e32 v152, v142, v152
	v_mfma_f32_32x32x16_bf16 v[66:81], v[70:73], v[128:131], 0
	ds_read_b128 v[162:165], v185 offset:32768
	ds_read_b128 v[166:169], v185 offset:45056
	v_add_f32_e32 v152, v135, v152
	v_add_f32_e32 v152, v137, v152
	v_add_f32_e32 v152, v138, v152
	v_add_f32_e32 v152, v139, v152
	v_add_f32_e32 v152, v132, v152
	v_add_f32_e32 v152, v133, v152
	v_add_f32_e32 v152, v134, v152
	s_waitcnt lgkmcnt(2)
	v_mfma_f32_32x32x16_bf16 v[82:97], v[204:207], v[124:127], v[82:97]
	v_add_f32_e32 v152, v136, v152
	v_exp_f32_e32 v208, v230
	v_exp_f32_e32 v150, v150
	v_exp_f32_e32 v151, v151
	v_exp_f32_e32 v210, v153
	v_exp_f32_e32 v211, v154
	v_exp_f32_e32 v233, v156
	v_mfma_f32_32x32x16_bf16 v[66:81], v[236:239], v[124:127], v[66:81]
	ds_read_b128 v[204:207], v186 offset:32768
	ds_read_b128 v[236:239], v186 offset:45056
	v_exp_f32_e32 v149, v149
	v_exp_f32_e32 v148, v148
	v_cvt_pk_bf16_f32 v153, v144, v145
	v_cvt_pk_bf16_f32 v154, v146, v147
	v_cvt_pk_bf16_f32 v156, v135, v137
	v_cvt_pk_bf16_f32 v230, v210, v211
	s_waitcnt lgkmcnt(2)
	v_mfma_f32_32x32x16_bf16 v[82:97], v[162:165], v[120:123], v[82:97]
	v_mfma_f32_32x32x16_bf16 v[66:81], v[166:169], v[120:123], v[66:81]
	ds_read_b128 v[162:165], v187 offset:32768
	ds_read_b128 v[166:169], v187 offset:45056
	s_waitcnt lgkmcnt(2)
	v_mfma_f32_32x32x16_bf16 v[82:97], v[204:207], v[116:119], v[82:97]
	v_mfma_f32_32x32x16_bf16 v[66:81], v[236:239], v[116:119], v[66:81]
	ds_read_b128 v[204:207], v188 offset:32768
	ds_read_b128 v[236:239], v188 offset:45056
	s_waitcnt lgkmcnt(2)
	v_mfma_f32_32x32x16_bf16 v[82:97], v[162:165], v[112:115], v[82:97]
	v_mfma_f32_32x32x16_bf16 v[66:81], v[166:169], v[112:115], v[66:81]
	ds_read_b128 v[162:165], v189 offset:32768
	ds_read_b128 v[166:169], v189 offset:45056
	s_waitcnt lgkmcnt(2)
	v_mfma_f32_32x32x16_bf16 v[82:97], v[204:207], v[108:111], v[82:97]
	v_mfma_f32_32x32x16_bf16 v[66:81], v[236:239], v[108:111], v[66:81]
	ds_read_b128 v[204:207], v190 offset:32768
	ds_read_b128 v[236:239], v190 offset:45056
	s_waitcnt lgkmcnt(2)
	v_mfma_f32_32x32x16_bf16 v[82:97], v[162:165], v[104:107], v[82:97]
	v_mfma_f32_32x32x16_bf16 v[66:81], v[166:169], v[104:107], v[66:81]
	ds_read_b128 v[162:165], v191 offset:32768
	ds_read_b128 v[166:169], v191 offset:45056
	ds_read_b128 v[240:243], v192
	s_waitcnt lgkmcnt(3)
	v_mfma_f32_32x32x16_bf16 v[82:97], v[204:207], v[100:103], v[82:97]
	v_mfma_f32_32x32x16_bf16 v[66:81], v[236:239], v[100:103], v[66:81]
	ds_read_b128 v[204:207], v194 offset:32768
	ds_read_b128 v[236:239], v194 offset:45056
	ds_read_b128 v[244:247], v176
	s_waitcnt lgkmcnt(3)
	v_mfma_f32_32x32x16_bf16 v[82:97], v[162:165], v[240:243], v[82:97]
	v_mfma_f32_32x32x16_bf16 v[66:81], v[166:169], v[240:243], v[66:81]
	ds_read_b128 v[162:165], v195 offset:32768
	ds_read_b128 v[166:169], v195 offset:45056
	ds_read_b128 v[240:243], v177
	s_waitcnt lgkmcnt(3)
	v_mfma_f32_32x32x16_bf16 v[82:97], v[204:207], v[244:247], v[82:97]
	v_mfma_f32_32x32x16_bf16 v[66:81], v[236:239], v[244:247], v[66:81]
	ds_read_b128 v[204:207], v196 offset:32768
	ds_read_b128 v[236:239], v196 offset:45056
	ds_read_b128 v[244:247], v175
	s_waitcnt lgkmcnt(3)
	v_mfma_f32_32x32x16_bf16 v[82:97], v[162:165], v[240:243], v[82:97]
	v_mfma_f32_32x32x16_bf16 v[66:81], v[166:169], v[240:243], v[66:81]
	s_waitcnt lgkmcnt(0)
	v_mfma_f32_32x32x16_bf16 v[82:97], v[204:207], v[244:247], v[82:97]
	v_exp_f32_e32 v204, v157
	v_exp_f32_e32 v205, v158
	v_exp_f32_e32 v206, v159
	v_exp_f32_e32 v207, v229
	v_add_f32_e32 v152, v204, v152
	v_add_f32_e32 v152, v205, v152
	v_add_f32_e32 v152, v206, v152
	v_add_f32_e32 v152, v207, v152
	v_add_f32_e32 v152, v208, v152
	v_add_f32_e32 v152, v150, v152
	v_exp_f32_e32 v229, v155
	v_add_f32_e32 v152, v151, v152
	v_add_f32_e32 v152, v209, v152
	v_add_f32_e32 v152, v210, v152
	v_mfma_f32_32x32x16_bf16 v[66:81], v[236:239], v[244:247], v[66:81]
	v_exp_f32_e32 v237, v231
	v_add_f32_e32 v152, v211, v152
	v_exp_f32_e32 v238, v232
	v_add_f32_e32 v152, v229, v152
	v_add_f32_e32 v152, v233, v152
	v_add_f32_e32 v152, v149, v152
	v_add_f32_e32 v152, v237, v152
	v_add_f32_e32 v152, v238, v152
	v_add_f32_e32 v235, v148, v152
	v_mov_b32_e32 v236, v235
	v_cvt_pk_bf16_f32 v152, v141, v143
	v_cvt_pk_bf16_f32 v155, v140, v142
	v_permlane32_swap_b32_e32 v235, v236
	v_permlane32_swap_b32_e32 v152, v154
	v_permlane32_swap_b32_e32 v153, v155
	v_cvt_pk_bf16_f32 v157, v138, v139
	v_cvt_pk_bf16_f32 v158, v132, v133
	v_cvt_pk_bf16_f32 v159, v134, v136
	v_cvt_pk_bf16_f32 v204, v204, v205
	v_cvt_pk_bf16_f32 v205, v206, v207
	v_cvt_pk_bf16_f32 v206, v208, v150
	v_cvt_pk_bf16_f32 v207, v151, v209
	v_cvt_pk_bf16_f32 v231, v229, v233
	v_cvt_pk_bf16_f32 v232, v149, v237
	v_cvt_pk_bf16_f32 v233, v238, v148
	v_permlane32_swap_b32_e32 v156, v158
	v_permlane32_swap_b32_e32 v157, v159
	v_permlane32_swap_b32_e32 v204, v206
	v_permlane32_swap_b32_e32 v205, v207
	v_permlane32_swap_b32_e32 v230, v232
	v_permlane32_swap_b32_e32 v231, v233
	ds_read_b64_tr_b16 v[238:239], v199 offset:0
	ds_read_b64_tr_b16 v[240:241], v199 offset:0x800
	ds_read_b64_tr_b16 v[242:243], v199 offset:0x1000
	ds_read_b64_tr_b16 v[244:245], v199 offset:0x1800
	ds_read_b64_tr_b16 v[246:247], v199 offset:0x2000
	ds_read_b64_tr_b16 v[248:249], v199 offset:0x2800
	ds_read_b64_tr_b16 v[208:209], v199 offset:0x3000
	ds_read_b64_tr_b16 v[210:211], v199 offset:0x3800
	s_nop 0
	s_waitcnt lgkmcnt(6)
	v_mfma_f32_32x32x16_bf16 v[2:17], v[152:155], v[238:241], v[2:17]
	s_waitcnt lgkmcnt(4)
	v_mfma_f32_32x32x16_bf16 v[2:17], v[156:159], v[242:245], v[2:17]
	s_waitcnt lgkmcnt(2)
	v_mfma_f32_32x32x16_bf16 v[2:17], v[204:207], v[246:249], v[2:17]
	s_waitcnt lgkmcnt(0)
	v_mfma_f32_32x32x16_bf16 v[2:17], v[230:233], v[208:211], v[2:17]
	ds_read_b64_tr_b16 v[208:209], v199 offset:0x200
	ds_read_b64_tr_b16 v[210:211], v199 offset:0xa00
	ds_read_b64_tr_b16 v[238:239], v199 offset:0x1200
	ds_read_b64_tr_b16 v[240:241], v199 offset:0x1a00
	ds_read_b64_tr_b16 v[242:243], v199 offset:0x2200
	ds_read_b64_tr_b16 v[244:245], v199 offset:0x2a00
	ds_read_b64_tr_b16 v[246:247], v199 offset:0x3200
	ds_read_b64_tr_b16 v[248:249], v199 offset:0x3a00
	s_nop 0
	s_waitcnt lgkmcnt(6)
	v_mfma_f32_32x32x16_bf16 v[50:65], v[152:155], v[208:211], v[50:65]
	ds_read_b64_tr_b16 v[208:209], v199 offset:0x400
	ds_read_b64_tr_b16 v[210:211], v199 offset:0xc00
	s_waitcnt lgkmcnt(6)
	v_mfma_f32_32x32x16_bf16 v[50:65], v[156:159], v[238:241], v[50:65]
	ds_read_b64_tr_b16 v[238:239], v199 offset:0x1400
	ds_read_b64_tr_b16 v[240:241], v199 offset:0x1c00
	s_waitcnt lgkmcnt(6)
	v_mfma_f32_32x32x16_bf16 v[50:65], v[204:207], v[242:245], v[50:65]
	ds_read_b64_tr_b16 v[242:243], v199 offset:0x2400
	ds_read_b64_tr_b16 v[244:245], v199 offset:0x2c00
	s_waitcnt lgkmcnt(6)
	v_mfma_f32_32x32x16_bf16 v[50:65], v[230:233], v[246:249], v[50:65]
	ds_read_b64_tr_b16 v[246:247], v199 offset:0x3400
	ds_read_b64_tr_b16 v[248:249], v199 offset:0x3c00
	s_waitcnt lgkmcnt(6)
	v_mfma_f32_32x32x16_bf16 v[34:49], v[152:155], v[208:211], v[34:49]
	ds_read_b64_tr_b16 v[208:209], v199 offset:0x600
	ds_read_b64_tr_b16 v[210:211], v199 offset:0xe00
	s_waitcnt lgkmcnt(6)
	v_mfma_f32_32x32x16_bf16 v[34:49], v[156:159], v[238:241], v[34:49]
	ds_read_b64_tr_b16 v[238:239], v199 offset:0x1600
	ds_read_b64_tr_b16 v[240:241], v199 offset:0x1e00
	s_waitcnt lgkmcnt(6)
	v_mfma_f32_32x32x16_bf16 v[34:49], v[204:207], v[242:245], v[34:49]
	ds_read_b64_tr_b16 v[242:243], v199 offset:0x2600
	ds_read_b64_tr_b16 v[244:245], v199 offset:0x2e00
	s_waitcnt lgkmcnt(6)
	v_mfma_f32_32x32x16_bf16 v[34:49], v[230:233], v[246:249], v[34:49]
	ds_read_b64_tr_b16 v[246:247], v199 offset:0x3600
	ds_read_b64_tr_b16 v[248:249], v199 offset:0x3e00
	s_waitcnt lgkmcnt(6)
	v_mfma_f32_32x32x16_bf16 v[18:33], v[152:155], v[208:211], v[18:33]
	v_max_f32_e32 v152, v83, v83
	v_max_f32_e32 v153, v82, v82
	v_max_f32_e32 v152, v153, v152
	v_max3_f32 v152, v152, v84, v85
	v_max3_f32 v152, v152, v86, v87
	v_max3_f32 v152, v152, v88, v89
	v_max3_f32 v152, v152, v90, v91
	v_max3_f32 v152, v152, v92, v93
	v_max3_f32 v152, v152, v94, v95
	s_waitcnt lgkmcnt(4)
	v_mfma_f32_32x32x16_bf16 v[18:33], v[156:159], v[238:241], v[18:33]
	v_max3_f32 v152, v152, v96, v97
	v_max3_f32 v152, v152, v66, v67
	v_max3_f32 v152, v152, v68, v69
	v_max3_f32 v152, v152, v70, v71
	v_max3_f32 v152, v152, v72, v73
	v_max3_f32 v152, v152, v74, v75
	v_max3_f32 v152, v152, v76, v77
	v_max3_f32 v152, v152, v78, v79
	s_waitcnt lgkmcnt(2)
	v_mfma_f32_32x32x16_bf16 v[18:33], v[204:207], v[242:245], v[18:33]
	v_max3_f32 v152, v152, v80, v81
	v_mov_b32_e32 v153, v152
	s_nop 1
	v_permlane32_swap_b32_e32 v152, v153
	v_max_f32_e32 v153, v153, v153
	v_max_f32_e32 v152, v152, v152
	v_max_f32_e32 v152, v152, v153
	v_sub_f32_e32 v153, v152, v214
	v_cmp_ge_f32_e32 vcc, s5, v153
	v_max_f32_e32 v153, v214, v214
	v_max_f32_e32 v153, v153, v152
	s_waitcnt lgkmcnt(0)
	v_mfma_f32_32x32x16_bf16 v[18:33], v[230:233], v[246:249], v[18:33]
	v_sub_f32_e32 v152, v214, v153
	v_mul_f32_e32 v152, 0x3dd53b94, v152
	v_exp_f32_e32 v152, v152
	s_cmp_eq_u64 vcc, exec
	s_cselect_b64 s[40:41], -1, 0
	v_cndmask_b32_e64 v152, v152, 1.0, s[40:41]
	s_nop 0
	v_cmp_gt_f32_e32 vcc, 1.0, v152
	s_cbranch_vccz .LBB0_863
	s_and_saveexec_b64 s[0:1], s[38:39]
	ds_write_b32 v197, v152 offset:128
	s_or_b64 exec, exec, s[0:1]
	s_waitcnt lgkmcnt(0)
	ds_read_b128 v[132:135], v193 offset:224
	ds_read_b128 v[136:139], v193 offset:192
	ds_read_b128 v[140:143], v193 offset:160
	ds_read_b128 v[144:147], v193 offset:128
	s_waitcnt lgkmcnt(3)
	v_pk_mul_f32 v[16:17], v[16:17], v[134:135]
	s_waitcnt lgkmcnt(2)
	v_pk_mul_f32 v[12:13], v[12:13], v[138:139]
	s_waitcnt lgkmcnt(1)
	v_pk_mul_f32 v[8:9], v[8:9], v[142:143]
	s_waitcnt lgkmcnt(0)
	v_pk_mul_f32 v[4:5], v[4:5], v[146:147]
	v_pk_mul_f32 v[14:15], v[14:15], v[132:133]
	v_pk_mul_f32 v[10:11], v[10:11], v[136:137]
	v_pk_mul_f32 v[6:7], v[6:7], v[140:141]
	v_pk_mul_f32 v[2:3], v[2:3], v[144:145]
	v_pk_mul_f32 v[64:65], v[64:65], v[134:135]
	v_pk_mul_f32 v[60:61], v[60:61], v[138:139]
	v_pk_mul_f32 v[56:57], v[56:57], v[142:143]
	v_pk_mul_f32 v[52:53], v[52:53], v[146:147]
	v_pk_mul_f32 v[62:63], v[62:63], v[132:133]
	v_pk_mul_f32 v[58:59], v[58:59], v[136:137]
	v_pk_mul_f32 v[54:55], v[54:55], v[140:141]
	v_pk_mul_f32 v[50:51], v[50:51], v[144:145]
	v_pk_mul_f32 v[48:49], v[48:49], v[134:135]
	v_pk_mul_f32 v[44:45], v[44:45], v[138:139]
	v_pk_mul_f32 v[40:41], v[40:41], v[142:143]
	v_pk_mul_f32 v[36:37], v[36:37], v[146:147]
	v_pk_mul_f32 v[46:47], v[46:47], v[132:133]
	v_pk_mul_f32 v[42:43], v[42:43], v[136:137]
	v_pk_mul_f32 v[38:39], v[38:39], v[140:141]
	v_pk_mul_f32 v[34:35], v[34:35], v[144:145]
	v_pk_mul_f32 v[32:33], v[32:33], v[134:135]
	v_pk_mul_f32 v[28:29], v[28:29], v[138:139]
	v_pk_mul_f32 v[24:25], v[24:25], v[142:143]
	v_pk_mul_f32 v[20:21], v[20:21], v[146:147]
	v_pk_mul_f32 v[30:31], v[30:31], v[132:133]
	v_pk_mul_f32 v[26:27], v[26:27], v[136:137]
	v_pk_mul_f32 v[22:23], v[22:23], v[140:141]
	v_pk_mul_f32 v[18:19], v[18:19], v[144:145]
.LBB0_863:
	v_cndmask_b32_e64 v214, v153, v214, s[40:41]
	v_mul_f32_e32 v138, 0xbdd53b94, v214
	v_mov_b32_e32 v139, v138
	v_fmamk_f32 v82, v82, 0x3dd53b94, v138
	v_fmamk_f32 v83, v83, 0x3dd53b94, v138
	v_fmamk_f32 v84, v84, 0x3dd53b94, v138
	v_fmamk_f32 v85, v85, 0x3dd53b94, v138
	v_fmamk_f32 v86, v86, 0x3dd53b94, v138
	v_fmamk_f32 v87, v87, 0x3dd53b94, v138
	v_fmamk_f32 v88, v88, 0x3dd53b94, v138
	v_fmamk_f32 v89, v89, 0x3dd53b94, v138
	v_fmamk_f32 v90, v90, 0x3dd53b94, v138
	v_fmamk_f32 v91, v91, 0x3dd53b94, v138
	v_fmamk_f32 v92, v92, 0x3dd53b94, v138
	v_fmamk_f32 v93, v93, 0x3dd53b94, v138
	v_fmamk_f32 v94, v94, 0x3dd53b94, v138
	v_fmamk_f32 v95, v95, 0x3dd53b94, v138
	v_fmamk_f32 v96, v96, 0x3dd53b94, v138
	v_fmac_f32_e32 v139, 0x3dd53b94, v97
	v_exp_f32_e32 v153, v82
	v_exp_f32_e32 v154, v83
	v_exp_f32_e32 v230, v84
	v_exp_f32_e32 v231, v85
	v_exp_f32_e32 v232, v86
	v_exp_f32_e32 v233, v87
	v_exp_f32_e32 v155, v88
	v_exp_f32_e32 v229, v89
	v_exp_f32_e32 v151, v90
	v_exp_f32_e32 v156, v91
	v_exp_f32_e32 v157, v92
	v_exp_f32_e32 v158, v93
	v_exp_f32_e32 v148, v94
	v_exp_f32_e32 v149, v95
	v_exp_f32_e32 v150, v96
	v_exp_f32_e32 v159, v139
	v_pk_fma_f32 v[144:145], v[66:67], s[30:31], v[138:139] op_sel_hi:[1,0,0]
	v_add_f32_e32 v66, v227, v228
	v_fmac_f32_e32 v66, v213, v198
	v_add_f32_e32 v198, v235, v236
	s_addk_i32 s12, 0x80
	s_addk_i32 s13, 0x80
	v_pk_fma_f32 v[142:143], v[68:69], s[30:31], v[138:139] op_sel_hi:[1,0,0]
	v_pk_fma_f32 v[136:137], v[70:71], s[30:31], v[138:139] op_sel_hi:[1,0,0]
	v_pk_fma_f32 v[134:135], v[72:73], s[30:31], v[138:139] op_sel_hi:[1,0,0]
	v_pk_fma_f32 v[132:133], v[74:75], s[30:31], v[138:139] op_sel_hi:[1,0,0]
	v_pk_fma_f32 v[146:147], v[76:77], s[30:31], v[138:139] op_sel_hi:[1,0,0]
	v_pk_fma_f32 v[140:141], v[78:79], s[30:31], v[138:139] op_sel_hi:[1,0,0]
	v_pk_fma_f32 v[138:139], v[80:81], s[30:31], v[138:139] op_sel_hi:[1,0,0]
	v_fmac_f32_e32 v198, v66, v234
	s_cmp_gt_u32 s11, 32
	s_waitcnt vmcnt(0) lgkmcnt(0)
	s_barrier
	s_cbranch_scc1 .LBB0_865
	v_mov_b32_e32 v213, v152
	s_branch .LBB0_855
.LBB0_865:
	s_add_i32 m0, s100, 0x4000
	s_nop 0
	global_load_lds_dwordx4 v178, s[14:15]
	s_add_i32 m0, s100, 0x4400
	s_nop 0
	global_load_lds_dwordx4 v179, s[14:15]
	ds_read_b128 v[66:69], v183 offset:57344
	ds_read_b128 v[70:73], v226 offset:57344
	v_add_f32_e32 v98, 0, v153
	v_add_f32_e32 v98, v154, v98
	v_add_f32_e32 v98, v230, v98
	s_waitcnt lgkmcnt(1)
	v_mfma_f32_32x32x16_bf16 v[82:97], v[66:69], v[128:131], 0
	v_add_f32_e32 v98, v231, v98
	v_add_f32_e32 v98, v232, v98
	v_add_f32_e32 v98, v233, v98
	v_add_f32_e32 v98, v155, v98
	v_add_f32_e32 v98, v229, v98
	v_add_f32_e32 v98, v151, v98
	v_add_f32_e32 v98, v156, v98
	s_waitcnt lgkmcnt(0)
	v_mfma_f32_32x32x16_bf16 v[66:81], v[70:73], v[128:131], 0
	ds_read_b128 v[128:131], v184 offset:57344
	ds_read_b128 v[162:165], v225 offset:57344
	v_add_f32_e32 v98, v157, v98
	v_add_f32_e32 v98, v158, v98
	v_add_f32_e32 v98, v148, v98
	v_add_f32_e32 v98, v149, v98
	v_add_f32_e32 v98, v150, v98
	v_add_f32_e32 v98, v159, v98
	s_waitcnt lgkmcnt(1)
	v_mfma_f32_32x32x16_bf16 v[82:97], v[128:131], v[124:127], v[82:97]
	s_waitcnt lgkmcnt(0)
	v_mfma_f32_32x32x16_bf16 v[66:81], v[162:165], v[124:127], v[66:81]
	ds_read_b128 v[124:127], v185 offset:57344
	ds_read_b128 v[128:131], v224 offset:57344
	s_waitcnt lgkmcnt(1)
	v_mfma_f32_32x32x16_bf16 v[82:97], v[124:127], v[120:123], v[82:97]
	s_waitcnt lgkmcnt(0)
	v_mfma_f32_32x32x16_bf16 v[66:81], v[128:131], v[120:123], v[66:81]
	ds_read_b128 v[120:123], v186 offset:57344
	ds_read_b128 v[124:127], v223 offset:57344
	s_waitcnt lgkmcnt(1)
	v_mfma_f32_32x32x16_bf16 v[82:97], v[120:123], v[116:119], v[82:97]
	s_waitcnt lgkmcnt(0)
	v_mfma_f32_32x32x16_bf16 v[66:81], v[124:127], v[116:119], v[66:81]
	ds_read_b128 v[116:119], v187 offset:57344
	ds_read_b128 v[120:123], v222 offset:57344
	v_exp_f32_e32 v124, v139
	s_waitcnt lgkmcnt(1)
	v_mfma_f32_32x32x16_bf16 v[82:97], v[116:119], v[112:115], v[82:97]
	s_waitcnt lgkmcnt(0)
	v_mfma_f32_32x32x16_bf16 v[66:81], v[120:123], v[112:115], v[66:81]
	ds_read_b128 v[112:115], v188 offset:57344
	ds_read_b128 v[116:119], v221 offset:57344
	v_exp_f32_e32 v120, v147
	v_exp_f32_e32 v121, v140
	v_exp_f32_e32 v122, v141
	v_exp_f32_e32 v123, v138
	s_waitcnt lgkmcnt(1)
	v_mfma_f32_32x32x16_bf16 v[82:97], v[112:115], v[108:111], v[82:97]
	s_waitcnt lgkmcnt(0)
	v_mfma_f32_32x32x16_bf16 v[66:81], v[116:119], v[108:111], v[66:81]
	ds_read_b128 v[108:111], v189 offset:57344
	ds_read_b128 v[112:115], v220 offset:57344
	v_exp_f32_e32 v116, v135
	v_exp_f32_e32 v117, v132
	v_exp_f32_e32 v118, v133
	v_exp_f32_e32 v119, v146
	s_waitcnt lgkmcnt(1)
	v_mfma_f32_32x32x16_bf16 v[82:97], v[108:111], v[104:107], v[82:97]
	s_waitcnt lgkmcnt(0)
	v_mfma_f32_32x32x16_bf16 v[66:81], v[112:115], v[104:107], v[66:81]
	ds_read_b128 v[104:107], v190 offset:57344
	ds_read_b128 v[108:111], v219 offset:57344
	v_exp_f32_e32 v112, v143
	v_exp_f32_e32 v113, v136
	v_exp_f32_e32 v114, v137
	v_exp_f32_e32 v115, v134
	s_waitcnt lgkmcnt(1)
	v_mfma_f32_32x32x16_bf16 v[82:97], v[104:107], v[100:103], v[82:97]
	s_waitcnt lgkmcnt(0)
	v_mfma_f32_32x32x16_bf16 v[66:81], v[108:111], v[100:103], v[66:81]
	ds_read_b128 v[100:103], v191 offset:57344
	ds_read_b128 v[104:107], v218 offset:57344
	ds_read_b128 v[108:111], v192
	s_waitcnt lgkmcnt(0)
	v_mfma_f32_32x32x16_bf16 v[82:97], v[100:103], v[108:111], v[82:97]
	v_mfma_f32_32x32x16_bf16 v[66:81], v[104:107], v[108:111], v[66:81]
	ds_read_b128 v[100:103], v194 offset:57344
	ds_read_b128 v[104:107], v217 offset:57344
	ds_read_b128 v[108:111], v176
	s_waitcnt lgkmcnt(0)
	v_mfma_f32_32x32x16_bf16 v[82:97], v[100:103], v[108:111], v[82:97]
	v_mfma_f32_32x32x16_bf16 v[66:81], v[104:107], v[108:111], v[66:81]
	ds_read_b128 v[100:103], v195 offset:57344
	ds_read_b128 v[104:107], v216 offset:57344
	ds_read_b128 v[108:111], v177
	s_waitcnt lgkmcnt(0)
	v_mfma_f32_32x32x16_bf16 v[82:97], v[100:103], v[108:111], v[82:97]
	v_mfma_f32_32x32x16_bf16 v[66:81], v[104:107], v[108:111], v[66:81]
	ds_read_b128 v[100:103], v196 offset:57344
	ds_read_b128 v[104:107], v215 offset:57344
	ds_read_b128 v[108:111], v175
	s_waitcnt lgkmcnt(0)
	v_mfma_f32_32x32x16_bf16 v[82:97], v[100:103], v[108:111], v[82:97]
	v_exp_f32_e32 v101, v144
	v_cvt_pk_bf16_f32 v102, v153, v154
	v_cvt_pk_bf16_f32 v103, v230, v231
	v_add_f32_e32 v98, v101, v98
	v_mfma_f32_32x32x16_bf16 v[66:81], v[104:107], v[108:111], v[66:81]
	v_exp_f32_e32 v110, v145
	v_exp_f32_e32 v111, v142
	v_cvt_pk_bf16_f32 v104, v232, v233
	v_cvt_pk_bf16_f32 v105, v155, v229
	v_add_f32_e32 v98, v110, v98
	v_add_f32_e32 v98, v111, v98
	v_add_f32_e32 v98, v112, v98
	v_add_f32_e32 v98, v113, v98
	v_add_f32_e32 v98, v114, v98
	v_add_f32_e32 v98, v115, v98
	v_add_f32_e32 v98, v116, v98
	v_add_f32_e32 v98, v117, v98
	v_add_f32_e32 v98, v118, v98
	v_add_f32_e32 v98, v119, v98
	v_add_f32_e32 v98, v120, v98
	v_add_f32_e32 v98, v121, v98
	v_add_f32_e32 v98, v122, v98
	v_add_f32_e32 v98, v123, v98
	v_add_f32_e32 v98, v124, v98
	v_mov_b32_e32 v100, v98
	s_nop 1
	v_permlane32_swap_b32_e32 v98, v100
	v_permlane32_swap_b32_e32 v102, v104
	v_cvt_pk_bf16_f32 v106, v151, v156
	v_cvt_pk_bf16_f32 v107, v157, v158
	v_cvt_pk_bf16_f32 v108, v148, v149
	v_cvt_pk_bf16_f32 v109, v150, v159
	v_cvt_pk_bf16_f32 v110, v101, v110
	v_cvt_pk_bf16_f32 v111, v111, v112
	v_cvt_pk_bf16_f32 v112, v113, v114
	v_cvt_pk_bf16_f32 v113, v115, v116
	v_cvt_pk_bf16_f32 v114, v117, v118
	v_cvt_pk_bf16_f32 v115, v119, v120
	v_cvt_pk_bf16_f32 v116, v121, v122
	v_cvt_pk_bf16_f32 v117, v123, v124
	v_permlane32_swap_b32_e32 v103, v105
	v_permlane32_swap_b32_e32 v106, v108
	v_permlane32_swap_b32_e32 v107, v109
	v_permlane32_swap_b32_e32 v110, v112
	v_permlane32_swap_b32_e32 v111, v113
	v_permlane32_swap_b32_e32 v114, v116
	v_permlane32_swap_b32_e32 v115, v117
	ds_read_b64_tr_b16 v[118:119], v174 offset:0
	ds_read_b64_tr_b16 v[120:121], v174 offset:0x800
	ds_read_b64_tr_b16 v[122:123], v174 offset:0x1000
	ds_read_b64_tr_b16 v[124:125], v174 offset:0x1800
	ds_read_b64_tr_b16 v[126:127], v174 offset:0x2000
	ds_read_b64_tr_b16 v[128:129], v174 offset:0x2800
	ds_read_b64_tr_b16 v[130:131], v174 offset:0x3000
	ds_read_b64_tr_b16 v[132:133], v174 offset:0x3800
	s_waitcnt lgkmcnt(0)
	s_nop 0
	v_mfma_f32_32x32x16_bf16 v[2:17], v[102:105], v[118:121], v[2:17]
	ds_read_b64_tr_b16 v[118:119], v174 offset:0x200
	ds_read_b64_tr_b16 v[120:121], v174 offset:0xa00
	v_mfma_f32_32x32x16_bf16 v[2:17], v[106:109], v[122:125], v[2:17]
	ds_read_b64_tr_b16 v[122:123], v174 offset:0x1200
	ds_read_b64_tr_b16 v[124:125], v174 offset:0x1a00
	v_mfma_f32_32x32x16_bf16 v[2:17], v[110:113], v[126:129], v[2:17]
	ds_read_b64_tr_b16 v[126:127], v174 offset:0x2200
	ds_read_b64_tr_b16 v[128:129], v174 offset:0x2a00
	v_mfma_f32_32x32x16_bf16 v[2:17], v[114:117], v[130:133], v[2:17]
	ds_read_b64_tr_b16 v[130:131], v174 offset:0x3200
	ds_read_b64_tr_b16 v[132:133], v174 offset:0x3a00
	s_waitcnt lgkmcnt(0)
	v_mfma_f32_32x32x16_bf16 v[50:65], v[102:105], v[118:121], v[50:65]
	ds_read_b64_tr_b16 v[118:119], v174 offset:0x400
	ds_read_b64_tr_b16 v[120:121], v174 offset:0xc00
	v_mfma_f32_32x32x16_bf16 v[50:65], v[106:109], v[122:125], v[50:65]
	ds_read_b64_tr_b16 v[122:123], v174 offset:0x1400
	ds_read_b64_tr_b16 v[124:125], v174 offset:0x1c00
	v_mfma_f32_32x32x16_bf16 v[50:65], v[110:113], v[126:129], v[50:65]
	ds_read_b64_tr_b16 v[126:127], v174 offset:0x2400
	ds_read_b64_tr_b16 v[128:129], v174 offset:0x2c00
	v_mfma_f32_32x32x16_bf16 v[50:65], v[114:117], v[130:133], v[50:65]
	ds_read_b64_tr_b16 v[130:131], v174 offset:0x3400
	ds_read_b64_tr_b16 v[132:133], v174 offset:0x3c00
	s_waitcnt lgkmcnt(0)
	v_mfma_f32_32x32x16_bf16 v[34:49], v[102:105], v[118:121], v[34:49]
	ds_read_b64_tr_b16 v[118:119], v174 offset:0x600
	ds_read_b64_tr_b16 v[120:121], v174 offset:0xe00
	v_mfma_f32_32x32x16_bf16 v[34:49], v[106:109], v[122:125], v[34:49]
	ds_read_b64_tr_b16 v[122:123], v174 offset:0x1600
	ds_read_b64_tr_b16 v[124:125], v174 offset:0x1e00
	v_mfma_f32_32x32x16_bf16 v[34:49], v[110:113], v[126:129], v[34:49]
	ds_read_b64_tr_b16 v[126:127], v174 offset:0x2600
	ds_read_b64_tr_b16 v[128:129], v174 offset:0x2e00
	v_mfma_f32_32x32x16_bf16 v[34:49], v[114:117], v[130:133], v[34:49]
	ds_read_b64_tr_b16 v[130:131], v174 offset:0x3600
	ds_read_b64_tr_b16 v[132:133], v174 offset:0x3e00
	s_waitcnt lgkmcnt(0)
	v_mfma_f32_32x32x16_bf16 v[18:33], v[102:105], v[118:121], v[18:33]
	v_max_f32_e32 v101, v83, v83
	v_max_f32_e32 v102, v82, v82
	v_max_f32_e32 v101, v102, v101
	v_max3_f32 v101, v101, v84, v85
	v_max3_f32 v101, v101, v86, v87
	v_max3_f32 v101, v101, v88, v89
	v_max3_f32 v101, v101, v90, v91
	v_max3_f32 v101, v101, v92, v93
	v_max3_f32 v101, v101, v94, v95
	v_mfma_f32_32x32x16_bf16 v[18:33], v[106:109], v[122:125], v[18:33]
	v_max3_f32 v101, v101, v96, v97
	v_max3_f32 v101, v101, v66, v67
	v_max3_f32 v101, v101, v68, v69
	v_max3_f32 v101, v101, v70, v71
	v_max3_f32 v101, v101, v72, v73
	v_max3_f32 v101, v101, v74, v75
	v_max3_f32 v101, v101, v76, v77
	v_max3_f32 v101, v101, v78, v79
	v_mfma_f32_32x32x16_bf16 v[18:33], v[110:113], v[126:129], v[18:33]
	v_max3_f32 v101, v101, v80, v81
	v_mov_b32_e32 v102, v101
	s_nop 1
	v_permlane32_swap_b32_e32 v101, v102
	v_max_f32_e32 v102, v102, v102
	v_max_f32_e32 v101, v101, v101
	v_max_f32_e32 v101, v101, v102
	v_sub_f32_e32 v102, v101, v214
	v_cmp_ge_f32_e32 vcc, s5, v102
	v_max_f32_e32 v102, v214, v214
	v_max_f32_e32 v102, v102, v101
	v_mfma_f32_32x32x16_bf16 v[18:33], v[114:117], v[130:133], v[18:33]
	v_sub_f32_e32 v101, v214, v102
	v_mul_f32_e32 v101, 0x3dd53b94, v101
	v_exp_f32_e32 v101, v101
	s_cmp_eq_u64 vcc, exec
	s_cselect_b64 s[0:1], -1, 0
	v_cndmask_b32_e64 v101, v101, 1.0, s[0:1]
	v_cmp_gt_f32_e32 vcc, 1.0, v101
	s_waitcnt vmcnt(0)
	s_barrier
	s_cbranch_vccz .LBB0_869
	s_mov_b64 s[22:23], exec
	s_and_b64 s[8:9], s[22:23], s[38:39]
	v_mov_b32_e32 v241, v203
	v_mov_b32_e32 v242, v202
	s_mov_b64 exec, s[8:9]
	ds_write_b32 v197, v101 offset:128
	s_or_b64 exec, exec, s[22:23]
	s_waitcnt lgkmcnt(0)
	ds_read_b128 v[104:107], v193 offset:224
	ds_read_b128 v[108:111], v193 offset:192
	ds_read_b128 v[112:115], v193 offset:160
	ds_read_b128 v[116:119], v193 offset:128
	v_mov_b32_e32 v203, v201
	s_waitcnt lgkmcnt(3)
	v_pk_mul_f32 v[16:17], v[16:17], v[106:107]
	s_waitcnt lgkmcnt(2)
	v_pk_mul_f32 v[12:13], v[12:13], v[110:111]
	s_waitcnt lgkmcnt(1)
	v_pk_mul_f32 v[8:9], v[8:9], v[114:115]
	s_waitcnt lgkmcnt(0)
	v_pk_mul_f32 v[4:5], v[4:5], v[118:119]
	v_pk_mul_f32 v[14:15], v[14:15], v[104:105]
	v_pk_mul_f32 v[10:11], v[10:11], v[108:109]
	v_pk_mul_f32 v[6:7], v[6:7], v[112:113]
	v_pk_mul_f32 v[2:3], v[2:3], v[116:117]
	v_pk_mul_f32 v[64:65], v[64:65], v[106:107]
	v_pk_mul_f32 v[60:61], v[60:61], v[110:111]
	v_pk_mul_f32 v[56:57], v[56:57], v[114:115]
	v_pk_mul_f32 v[52:53], v[52:53], v[118:119]
	v_pk_mul_f32 v[62:63], v[62:63], v[104:105]
	v_pk_mul_f32 v[58:59], v[58:59], v[108:109]
	v_pk_mul_f32 v[54:55], v[54:55], v[112:113]
	v_pk_mul_f32 v[50:51], v[50:51], v[116:117]
	v_pk_mul_f32 v[48:49], v[48:49], v[106:107]
	v_pk_mul_f32 v[44:45], v[44:45], v[110:111]
	v_pk_mul_f32 v[40:41], v[40:41], v[114:115]
	v_pk_mul_f32 v[36:37], v[36:37], v[118:119]
	v_pk_mul_f32 v[46:47], v[46:47], v[104:105]
	v_pk_mul_f32 v[42:43], v[42:43], v[108:109]
	v_pk_mul_f32 v[38:39], v[38:39], v[112:113]
	v_pk_mul_f32 v[34:35], v[34:35], v[116:117]
	v_pk_mul_f32 v[32:33], v[32:33], v[106:107]
	v_pk_mul_f32 v[28:29], v[28:29], v[110:111]
	v_pk_mul_f32 v[24:25], v[24:25], v[114:115]
	v_pk_mul_f32 v[20:21], v[20:21], v[118:119]
	v_pk_mul_f32 v[30:31], v[30:31], v[104:105]
	v_pk_mul_f32 v[26:27], v[26:27], v[108:109]
	v_pk_mul_f32 v[22:23], v[22:23], v[112:113]
	v_pk_mul_f32 v[18:19], v[18:19], v[116:117]
	s_branch .LBB0_870
